# XCD-local barrier: acquire buffer_inv issued right after the arrive atomic (overlaps the wait) instead of after the release is observed; global mode unchanged
# speedup vs baseline: 1.0163x; 1.0033x over previous
.LBB0_139:
	s_or_b64 exec, exec, s[8:9]
	s_cmp_lg_u32 s101, 0
	s_cbranch_scc1 .Lxw_3
	s_waitcnt vmcnt(0)
.Lxw_3:
.LBB0_140:
	s_or_b64 exec, exec, s[0:1]
	v_readlane_b32 s4, v255, 18
	v_readlane_b32 s5, v255, 19
	s_mov_b32 s0, 1
	s_mov_b64 s[6:7], 0
	s_and_b64 vcc, exec, s[4:5]
	s_waitcnt lgkmcnt(0)
	s_barrier
	s_cbranch_vccnz .LBB0_549

.LBB0_194:
	s_mov_b64 s[10:11], exec
	v_mbcnt_lo_u32_b32 v1, s10, 0
	v_mbcnt_hi_u32_b32 v1, s11, v1
	v_cmp_eq_u32_e32 vcc, 0, v1
	s_and_saveexec_b64 s[8:9], vcc
	s_cbranch_execz .LBB0_196
	s_bcnt1_i32_b64 s4, s[10:11]
	v_mov_b32_e32 v3, s4
	v_readlane_b32 s4, v254, 26
	v_readlane_b32 s5, v254, 27
	s_nop 4
	global_atomic_add v3, v177, v3, s[4:5] sc0
	s_cmp_lg_u32 s101, 0
	s_cbranch_scc0 .Lea_0
	buffer_inv sc1
.Lea_0:
.LBB0_196:
	s_or_b64 exec, exec, s[8:9]
	v_cvt_f32_u32_e32 v4, v2
	s_waitcnt vmcnt(0)
	v_readfirstlane_b32 s4, v3
	v_sub_u32_e32 v3, 0, v2
	v_rcp_iflag_f32_e32 v4, v4
	v_add_u32_e32 v5, s4, v1
	v_mul_f32_e32 v4, 0x4f7ffffe, v4
	v_cvt_u32_f32_e32 v4, v4
	v_mul_lo_u32 v1, v3, v4
	v_mul_hi_u32 v1, v4, v1
	v_add_u32_e32 v1, v4, v1
	v_mul_hi_u32 v1, v5, v1
	v_mul_lo_u32 v3, v1, v2
	v_sub_u32_e32 v3, v5, v3
	v_add_u32_e32 v4, 1, v1
	v_cmp_ge_u32_e32 vcc, v3, v2
	s_nop 1
	v_cndmask_b32_e32 v1, v1, v4, vcc
	v_sub_u32_e32 v4, v3, v2
	v_cndmask_b32_e32 v3, v3, v4, vcc
	v_add_u32_e32 v4, 1, v1
	v_cmp_ge_u32_e32 vcc, v3, v2
	v_add_u32_e32 v3, 1, v5
	s_nop 0
	v_cndmask_b32_e32 v1, v1, v4, vcc
	v_mul_lo_u32 v4, v2, v1
	v_add_u32_e32 v2, v4, v2
	v_cmp_ne_u32_e32 vcc, v3, v2
	s_and_saveexec_b64 s[4:5], vcc
	s_xor_b64 s[8:9], exec, s[4:5]
	s_cbranch_execz .LBB0_210
	v_readlane_b32 s4, v254, 28
	v_readlane_b32 s5, v254, 29
	s_waitcnt lgkmcnt(0)
	s_nop 3
	global_load_dword v0, v177, s[4:5] sc1
	s_waitcnt vmcnt(0)
	v_cmp_eq_u32_e32 vcc, v0, v1
	s_and_saveexec_b64 s[12:13], vcc
	s_cbranch_execz .LBB0_209
	s_mov_b32 s16, 1
	s_mov_b64 s[10:11], 0
	s_branch .LBB0_200

.LBB0_209:
	s_or_b64 exec, exec, s[12:13]
	s_cmp_lg_u32 s101, 0
	s_cbranch_scc1 .Lei_0
	s_waitcnt vmcnt(0)
	buffer_inv sc1
	s_waitcnt vmcnt(0)
.Lei_0:
.LBB0_210:
	s_andn2_saveexec_b64 s[4:5], s[8:9]
	s_cbranch_execz .LBB0_230
	s_mov_b64 s[8:9], exec
	s_cmp_lg_u32 s101, 0
	s_cbranch_scc1 .Lxl_0
	buffer_wbl2 sc1
	s_waitcnt lgkmcnt(0)
	s_waitcnt vmcnt(0)
	v_mbcnt_lo_u32_b32 v1, s8, 0
	v_mbcnt_hi_u32_b32 v1, s9, v1
	v_cmp_eq_u32_e32 vcc, 0, v1
	s_and_saveexec_b64 s[10:11], vcc
	s_cbranch_execz .LBB0_213
	s_bcnt1_i32_b64 s4, s[8:9]
	v_mov_b32_e32 v2, s4
	v_readlane_b32 s4, v254, 30
	v_readlane_b32 s5, v254, 31
	s_nop 4
	global_atomic_add v2, v177, v2, s[4:5] sc0

.Lxl_0:
	s_mov_b64 s[8:9], exec
	v_mbcnt_lo_u32_b32 v0, s8, 0
	v_mbcnt_hi_u32_b32 v0, s9, v0
	v_cmp_eq_u32_e32 vcc, 0, v0
	s_cmp_lg_u32 s101, 0
	s_cbranch_scc1 .Lxi_0
	s_waitcnt vmcnt(0)
	buffer_inv sc1
.Lxi_0:
	s_and_saveexec_b64 s[10:11], vcc
	s_cbranch_execz .LBB0_229
	s_bcnt1_i32_b64 s4, s[8:9]
	v_mov_b32_e32 v0, s4
	v_readlane_b32 s4, v254, 28
	v_readlane_b32 s5, v254, 29
	s_nop 4
	global_atomic_add v177, v0, s[4:5]
.LBB0_229:
	s_or_b64 exec, exec, s[10:11]
	s_cmp_lg_u32 s101, 0
	s_cbranch_scc1 .Lxw_0
	s_waitcnt vmcnt(0)
.Lxw_0:
.LBB0_230:
	s_or_b64 exec, exec, s[0:1]
	v_readlane_b32 s56, v253, 32
	s_xor_b64 s[0:1], s[6:7], -1
	v_readlane_b32 s70, v253, 46
	v_readlane_b32 s71, v253, 47
	v_writelane_b32 v255, s0, 18
	s_mov_b64 s[6:7], s[70:71]
	s_waitcnt lgkmcnt(0)
	v_writelane_b32 v255, s1, 19
	s_barrier
	s_add_u32 s8, s6, 0x12d00000
	v_mov_b32_e32 v24, v218
	s_movk_i32 s0, 0x100
	s_addc_u32 s9, s7, 0
	s_and_b32 s98, s2, 7
	s_mul_i32 s98, s98, 0xe00000
	s_add_u32 s8, s8, s98
	s_addc_u32 s9, s9, 0
	v_readlane_b32 s57, v253, 33
	v_cmp_gt_i32_e32 vcc, s0, v24
	v_readlane_b32 s58, v253, 34
	v_readlane_b32 s59, v253, 35
	v_readlane_b32 s60, v253, 36
	v_readlane_b32 s61, v253, 37
	v_readlane_b32 s62, v253, 38
	v_readlane_b32 s63, v253, 39
	v_readlane_b32 s64, v253, 40
	v_readlane_b32 s65, v253, 41
	v_readlane_b32 s66, v253, 42
	v_readlane_b32 s67, v253, 43
	v_readlane_b32 s68, v253, 44
	v_readlane_b32 s69, v253, 45
	s_and_saveexec_b64 s[0:1], vcc
	s_xor_b64 s[0:1], exec, s[0:1]
	s_cbranch_execz .LBB0_243
	v_lshlrev_b32_e32 v0, 3, v24
	v_and_b32_e32 v32, 0x3f8, v0
	v_lshlrev_b32_e32 v20, 2, v32
	global_load_dwordx4 v[0:3], v20, s[22:23] offset:16
	global_load_dwordx4 v[4:7], v20, s[22:23]
	global_load_dwordx4 v[8:11], v20, s[20:21] offset:16
	global_load_dwordx4 v[12:15], v20, s[20:21]
	global_load_dwordx4 v[16:19], v20, s[18:19] offset:16
	s_nop 0
	global_load_dwordx4 v[20:23], v20, s[18:19]
	s_add_u32 s12, s6, 0xa900000
	s_addc_u32 s13, s7, 0
	s_add_u32 s18, s6, 0xe900000
	s_addc_u32 s19, s7, 0
	v_ashrrev_i32_e32 v33, 7, v24
	s_mov_b64 s[20:21], s[2:3]
	s_branch .LBB0_234

.LBB0_344:
	s_mov_b64 s[8:9], exec
	v_mbcnt_lo_u32_b32 v1, s8, 0
	v_mbcnt_hi_u32_b32 v1, s9, v1
	v_cmp_eq_u32_e32 vcc, 0, v1
	s_and_saveexec_b64 s[6:7], vcc
	s_cbranch_execz .LBB0_346
	s_bcnt1_i32_b64 s4, s[8:9]
	v_mov_b32_e32 v3, s4
	v_readlane_b32 s4, v254, 26
	v_readlane_b32 s5, v254, 27
	s_nop 4
	global_atomic_add v3, v177, v3, s[4:5] sc0
	s_cmp_lg_u32 s101, 0
	s_cbranch_scc0 .Lea_1
	buffer_inv sc1
.Lea_1:
.LBB0_346:
	s_or_b64 exec, exec, s[6:7]
	v_cvt_f32_u32_e32 v4, v2
	s_waitcnt vmcnt(0)
	v_readfirstlane_b32 s4, v3
	v_sub_u32_e32 v3, 0, v2
	v_rcp_iflag_f32_e32 v4, v4
	v_add_u32_e32 v5, s4, v1
	v_mul_f32_e32 v4, 0x4f7ffffe, v4
	v_cvt_u32_f32_e32 v4, v4
	v_mul_lo_u32 v1, v3, v4
	v_mul_hi_u32 v1, v4, v1
	v_add_u32_e32 v1, v4, v1
	v_mul_hi_u32 v1, v5, v1
	v_mul_lo_u32 v3, v1, v2
	v_sub_u32_e32 v3, v5, v3
	v_add_u32_e32 v4, 1, v1
	v_cmp_ge_u32_e32 vcc, v3, v2
	s_nop 1
	v_cndmask_b32_e32 v1, v1, v4, vcc
	v_sub_u32_e32 v4, v3, v2
	v_cndmask_b32_e32 v3, v3, v4, vcc
	v_add_u32_e32 v4, 1, v1
	v_cmp_ge_u32_e32 vcc, v3, v2
	v_add_u32_e32 v3, 1, v5
	s_nop 0
	v_cndmask_b32_e32 v1, v1, v4, vcc
	v_mul_lo_u32 v4, v2, v1
	v_add_u32_e32 v2, v4, v2
	v_cmp_ne_u32_e32 vcc, v3, v2
	s_and_saveexec_b64 s[4:5], vcc
	s_xor_b64 s[6:7], exec, s[4:5]
	s_cbranch_execz .LBB0_360
	v_readlane_b32 s4, v254, 28
	v_readlane_b32 s5, v254, 29
	s_waitcnt lgkmcnt(0)
	s_nop 3
	global_load_dword v0, v177, s[4:5] sc1
	s_waitcnt vmcnt(0)
	v_cmp_eq_u32_e32 vcc, v0, v1
	s_and_saveexec_b64 s[8:9], vcc
	s_cbranch_execz .LBB0_359
	s_mov_b32 s16, 1
	s_mov_b64 s[10:11], 0
	s_branch .LBB0_350

.LBB0_359:
	s_or_b64 exec, exec, s[8:9]
	s_cmp_lg_u32 s101, 0
	s_cbranch_scc1 .Lei_1
	s_waitcnt vmcnt(0)
	buffer_inv sc1
	s_waitcnt vmcnt(0)
.Lei_1:
.LBB0_360:
	s_andn2_saveexec_b64 s[4:5], s[6:7]
	s_cbranch_execz .LBB0_380
	s_mov_b64 s[6:7], exec
	s_cmp_lg_u32 s101, 0
	s_cbranch_scc1 .Lxl_1
	buffer_wbl2 sc1
	s_waitcnt lgkmcnt(0)
	s_waitcnt vmcnt(0)
	v_mbcnt_lo_u32_b32 v1, s6, 0
	v_mbcnt_hi_u32_b32 v1, s7, v1
	v_cmp_eq_u32_e32 vcc, 0, v1
	s_and_saveexec_b64 s[8:9], vcc
	s_cbranch_execz .LBB0_363
	s_bcnt1_i32_b64 s4, s[6:7]
	v_mov_b32_e32 v2, s4
	v_readlane_b32 s4, v254, 30
	v_readlane_b32 s5, v254, 31
	s_nop 4
	global_atomic_add v2, v177, v2, s[4:5] sc0

.Lxl_1:
	s_mov_b64 s[6:7], exec
	v_mbcnt_lo_u32_b32 v0, s6, 0
	v_mbcnt_hi_u32_b32 v0, s7, v0
	v_cmp_eq_u32_e32 vcc, 0, v0
	s_cmp_lg_u32 s101, 0
	s_cbranch_scc1 .Lxi_1
	s_waitcnt vmcnt(0)
	buffer_inv sc1
.Lxi_1:
	s_and_saveexec_b64 s[8:9], vcc
	s_cbranch_execz .LBB0_379
	s_bcnt1_i32_b64 s4, s[6:7]
	v_mov_b32_e32 v0, s4
	v_readlane_b32 s4, v254, 28
	v_readlane_b32 s5, v254, 29
	s_nop 4
	global_atomic_add v177, v0, s[4:5]

.Lxw_1:
.LBB0_380:
	s_or_b64 exec, exec, s[0:1]
	v_readlane_b32 s56, v253, 32
	v_readlane_b32 s57, v253, 33
	v_readlane_b32 s70, v253, 46
	v_readlane_b32 s71, v253, 47
	v_readlane_b32 s4, v254, 36
	s_mov_b64 s[0:1], s[70:71]
	s_movk_i32 s20, 0x400
	s_waitcnt vmcnt(2)
	v_mov_b32_e32 v12, v218
	v_readlane_b32 s5, v254, 37
	v_readlane_b32 s50, v254, 57
	v_readlane_b32 s56, v254, 59
	s_waitcnt lgkmcnt(0)
	s_barrier
	s_and_b64 vcc, exec, s[4:5]
	v_readfirstlane_b32 s10, v12
	v_readlane_b32 s51, v254, 58
	v_readlane_b32 s57, v254, 60
	v_readlane_b32 s58, v253, 34
	v_readlane_b32 s59, v253, 35
	v_readlane_b32 s60, v253, 36
	v_readlane_b32 s61, v253, 37
	v_readlane_b32 s62, v253, 38
	v_readlane_b32 s63, v253, 39
	v_readlane_b32 s64, v253, 40
	v_readlane_b32 s65, v253, 41
	v_readlane_b32 s66, v253, 42
	v_readlane_b32 s67, v253, 43
	v_readlane_b32 s68, v253, 44
	v_readlane_b32 s69, v253, 45
	s_cbranch_vccz .LBB0_405
	v_lshlrev_b32_e32 v0, 4, v12
	v_add_u32_e32 v1, 0x2000, v0
	v_ashrrev_i32_e32 v2, 31, v1
	v_lshrrev_b32_e32 v2, 22, v2
	v_add_u32_e32 v2, v1, v2
	v_ashrrev_i32_e32 v2, 10, v2
	v_mul_i32_i24_e32 v3, 0x400, v2
	v_sub_u32_e32 v1, v1, v3
	v_lshrrev_b32_e32 v3, 4, v1
	v_bitop3_b32 v1, v3, v1, 32 bitop3:0x6c
	v_ashrrev_i32_e32 v3, 31, v1
	s_add_u32 s16, s0, 0xc00000
	v_lshrrev_b32_e32 v3, 26, v3
	s_addc_u32 s33, s1, 0
	v_add_u32_e32 v3, v1, v3
	v_lshlrev_b32_e32 v5, 3, v2
	s_add_u32 s4, s0, s52
	v_ashrrev_i32_e32 v4, 6, v3
	v_and_b32_e32 v5, -16, v5
	v_lshlrev_b32_e32 v2, 5, v2
	s_addc_u32 s5, s1, 0
	v_add_u32_e32 v5, v4, v5
	v_and_b32_e32 v13, 32, v2
	v_and_b32_e32 v2, 0xc0, v3
	s_add_u32 s34, s4, 0x5400000
	v_and_b32_e32 v4, 3, v4
	s_mov_b32 s4, 0x7fffffe0
	v_lshrrev_b32_e32 v6, 2, v5
	v_lshlrev_b32_e32 v7, 1, v5
	v_sub_u32_e32 v1, v1, v2
	v_and_or_b32 v4, v5, s4, v4
	v_and_b32_e32 v6, 4, v6
	v_and_b32_e32 v7, 24, v7
	v_ashrrev_i16_sdwa v1, v221, sext(v1) dst_sel:DWORD dst_unused:UNUSED_PAD src0_sel:DWORD src1_sel:BYTE_0
	v_or3_b32 v4, v4, v6, v7
	v_bfe_i32 v14, v1, 0, 16
	v_mul_lo_u32 v4, v4, s20
	v_add_u32_e32 v1, v13, v14
	v_mul_lo_u32 v15, v5, s20
	v_add_lshl_u32 v132, v4, v1, 1
	v_add_lshl_u32 v134, v1, v15, 1
	v_bfe_i32 v1, v12, 27, 1
	v_lshrrev_b32_e32 v1, 22, v1
	v_add_u32_e32 v1, v0, v1
	v_and_b32_e32 v1, 0xfffffc00, v1
	v_sub_u32_e32 v0, v0, v1
	v_lshrrev_b32_e32 v1, 4, v0
	v_ashrrev_i32_e32 v3, 31, v12
	v_bitop3_b32 v0, v1, v0, 32 bitop3:0x6c
	v_lshrrev_b32_e32 v3, 26, v3
	v_ashrrev_i32_e32 v1, 31, v0
	v_add_u32_e32 v3, v12, v3
	v_lshrrev_b32_e32 v1, 26, v1
	v_ashrrev_i32_e32 v3, 6, v3
	v_add_u32_e32 v1, v0, v1
	v_lshlrev_b32_e32 v4, 3, v3
	v_ashrrev_i32_e32 v2, 6, v1
	v_and_b32_e32 v4, -16, v4
	s_addc_u32 s35, s5, 0
	s_ashr_i32 s21, s20, 31
	v_add_u32_e32 v4, v2, v4
	v_and_b32_e32 v2, 3, v2
	s_lshl_b64 s[8:9], s[20:21], 9
	v_and_or_b32 v2, v4, s4, v2
	v_readlane_b32 s4, v254, 52
	v_readlane_b32 s13, v255, 6
	s_mul_i32 s4, s8, s4
	s_mul_hi_u32 s5, s8, s13
	s_add_i32 s12, s5, s4
	s_lshr_b64 s[4:5], s[20:21], 23
	v_readlane_b32 s24, v254, 47
	s_mul_i32 s5, s4, s13
	v_readlane_b32 s25, v254, 48
	v_and_b32_e32 v1, 0xc0, v1
	s_add_i32 s12, s12, s5
	s_mul_i32 s5, s8, s25
	s_mul_hi_u32 s18, s8, s24
	s_ashr_i32 s22, s10, 6
	v_lshrrev_b32_e32 v5, 2, v4
	v_lshlrev_b32_e32 v6, 1, v4
	v_sub_u32_e32 v0, v0, v1
	s_add_i32 s5, s18, s5
	s_mul_i32 s4, s4, s24
	s_ashr_i32 s11, s10, 8
	s_lshl_b64 s[6:7], s[20:21], 8
	s_lshl_b32 s36, s22, 10
	v_and_b32_e32 v5, 4, v5
	v_and_b32_e32 v6, 24, v6
	v_lshlrev_b32_e32 v3, 5, v3
	v_ashrrev_i16_sdwa v0, v221, sext(v0) dst_sel:DWORD dst_unused:UNUSED_PAD src0_sel:DWORD src1_sel:BYTE_0
	s_add_i32 s5, s5, s4
	s_mul_i32 s4, s8, s24
	v_or3_b32 v2, v2, v5, v6
	s_waitcnt vmcnt(1)
	v_and_b32_e32 v16, 32, v3
	v_bfe_i32 v17, v0, 0, 16
	s_add_u32 s30, s34, s4
	v_mul_lo_u32 v2, v2, s20
	v_add_u32_e32 v0, v16, v17
	s_addc_u32 s31, s35, s5
	s_add_i32 s37, s36, 0
	v_add_lshl_u32 v176, v2, v0, 1
	s_add_i32 m0, s37, 0x10000
	s_mul_i32 s13, s8, s13
	global_load_lds_dwordx4 v176, s[30:31]
	s_add_i32 m0, s37, 0x12000
	s_add_u32 s4, s30, s6
	global_load_lds_dwordx4 v132, s[30:31]
	s_addc_u32 s5, s31, s7
	s_add_i32 m0, s37, 0x14000
	v_mul_lo_u32 v18, v4, s20
	global_load_lds_dwordx4 v176, s[4:5]
	s_add_i32 m0, s37, 0x16000
	s_add_u32 s28, s16, s13
	v_mov_b32_e32 v133, v177
	s_addc_u32 s29, s33, s12
	s_add_i32 s38, s37, 0x2000
	v_add_lshl_u32 v136, v0, v18, 1
	v_lshl_add_u64 v[4:5], s[4:5], 0, v[176:177]
	v_lshl_add_u64 v[6:7], s[4:5], 0, v[132:133]
	global_load_lds_dwordx4 v132, s[4:5]
	s_mov_b32 m0, s37
	s_add_u32 s4, s28, s6
	global_load_lds_dwordx4 v136, s[28:29]
	s_mov_b32 m0, s38
	s_addc_u32 s5, s29, s7
	s_add_i32 s39, s37, 0x4000
	global_load_lds_dwordx4 v134, s[28:29]
	s_mov_b32 m0, s39
	s_add_i32 s48, s37, 0x6000
	global_load_lds_dwordx4 v136, s[4:5]
	s_mov_b32 m0, s48
	v_mov_b32_e32 v137, v177
	global_load_lds_dwordx4 v134, s[4:5]
	v_mov_b32_e32 v135, v177
	s_cmp_eq_u32 s11, 1
	v_lshl_add_u64 v[0:1], s[30:31], 0, v[176:177]
	v_lshl_add_u64 v[2:3], s[30:31], 0, v[132:133]
	v_lshl_add_u64 v[8:9], s[28:29], 0, v[136:137]
	v_lshl_add_u64 v[10:11], s[28:29], 0, v[134:135]
	s_cselect_b64 s[12:13], -1, 0
	s_cmp_lg_u32 s11, 1
	s_cbranch_scc1 .LBB0_383
	s_barrier

.Lxw_2:
.LBB0_457:
	s_or_b64 exec, exec, s[0:1]
	v_readlane_b32 s56, v253, 32
	v_readlane_b32 s68, v253, 44
	v_readlane_b32 s69, v253, 45
	v_readlane_b32 s70, v253, 46
	v_readlane_b32 s71, v253, 47
	v_readlane_b32 s4, v253, 50
	s_mov_b64 s[0:1], s[70:71]
	s_movk_i32 s20, 0xb00
	v_mov_b32_e32 v18, v218
	v_readlane_b32 s5, v253, 51
	v_readlane_b32 s68, v254, 57
	v_readlane_b32 s70, v254, 59
	s_waitcnt lgkmcnt(0)
	s_barrier
	s_and_b64 vcc, exec, s[4:5]
	v_readfirstlane_b32 s10, v18
	v_readlane_b32 s69, v254, 58
	v_readlane_b32 s71, v254, 60
	v_readlane_b32 s57, v253, 33
	v_readlane_b32 s58, v253, 34
	v_readlane_b32 s59, v253, 35
	v_readlane_b32 s60, v253, 36
	v_readlane_b32 s61, v253, 37
	v_readlane_b32 s62, v253, 38
	v_readlane_b32 s63, v253, 39
	v_readlane_b32 s64, v253, 40
	v_readlane_b32 s65, v253, 41
	v_readlane_b32 s66, v253, 42
	v_readlane_b32 s67, v253, 43
	s_cbranch_vccz .LBB0_498
	v_lshlrev_b32_e32 v0, 4, v18
	v_add_u32_e32 v1, 0x2000, v0
	v_ashrrev_i32_e32 v2, 31, v1
	v_lshrrev_b32_e32 v2, 22, v2
	v_add_u32_e32 v2, v1, v2
	v_ashrrev_i32_e32 v2, 10, v2
	v_mul_i32_i24_e32 v3, 0x400, v2
	v_sub_u32_e32 v1, v1, v3
	v_lshrrev_b32_e32 v3, 4, v1
	v_bitop3_b32 v1, v3, v1, 32 bitop3:0x6c
	v_ashrrev_i32_e32 v3, 31, v1
	s_add_u32 s33, s0, 0x12d00000
	v_lshrrev_b32_e32 v3, 26, v3
	s_addc_u32 s34, s1, 0
	v_add_u32_e32 v3, v1, v3
	v_lshlrev_b32_e32 v5, 3, v2
	s_add_u32 s4, s0, s52
	v_ashrrev_i32_e32 v4, 6, v3
	v_and_b32_e32 v5, -16, v5
	v_lshlrev_b32_e32 v2, 5, v2
	s_addc_u32 s5, s1, 0
	v_add_u32_e32 v5, v4, v5
	v_and_b32_e32 v12, 32, v2
	v_and_b32_e32 v2, 0xc0, v3
	s_add_u32 s35, s4, 0x5f00000
	v_and_b32_e32 v4, 3, v4
	s_mov_b32 s4, 0x7fffffe0
	v_lshrrev_b32_e32 v6, 2, v5
	v_lshlrev_b32_e32 v7, 1, v5
	v_sub_u32_e32 v1, v1, v2
	v_and_or_b32 v4, v5, s4, v4
	v_and_b32_e32 v6, 4, v6
	v_and_b32_e32 v7, 24, v7
	v_ashrrev_i16_sdwa v1, v221, sext(v1) dst_sel:DWORD dst_unused:UNUSED_PAD src0_sel:DWORD src1_sel:BYTE_0
	v_or3_b32 v4, v4, v6, v7
	v_bfe_i32 v13, v1, 0, 16
	v_mul_lo_u32 v4, v4, s20
	v_add_u32_e32 v1, v12, v13
	v_mul_lo_u32 v14, v5, s20
	v_add_lshl_u32 v156, v4, v1, 1
	v_add_lshl_u32 v158, v1, v14, 1
	v_bfe_i32 v1, v18, 27, 1
	v_lshrrev_b32_e32 v1, 22, v1
	v_add_u32_e32 v1, v0, v1
	v_and_b32_e32 v1, 0xfffffc00, v1
	v_sub_u32_e32 v0, v0, v1
	v_lshrrev_b32_e32 v1, 4, v0
	v_ashrrev_i32_e32 v3, 31, v18
	v_bitop3_b32 v0, v1, v0, 32 bitop3:0x6c
	v_lshrrev_b32_e32 v3, 26, v3
	v_ashrrev_i32_e32 v1, 31, v0
	v_add_u32_e32 v3, v18, v3
	v_lshrrev_b32_e32 v1, 26, v1
	v_ashrrev_i32_e32 v3, 6, v3
	v_add_u32_e32 v1, v0, v1
	v_lshlrev_b32_e32 v4, 3, v3
	v_ashrrev_i32_e32 v2, 6, v1
	v_and_b32_e32 v4, -16, v4
	s_addc_u32 s36, s5, 0
	s_ashr_i32 s21, s20, 31
	v_add_u32_e32 v4, v2, v4
	v_and_b32_e32 v2, 3, v2
	s_lshl_b64 s[8:9], s[20:21], 9
	v_and_or_b32 v2, v4, s4, v2
	v_readlane_b32 s4, v254, 53
	s_mul_i32 s4, s8, s4
	s_mul_hi_u32 s5, s8, s95
	s_add_i32 s12, s5, s4
	s_lshr_b64 s[4:5], s[20:21], 23
	v_readlane_b32 s22, v254, 50
	s_mul_i32 s5, s4, s95
	v_readlane_b32 s23, v254, 51
	v_and_b32_e32 v1, 0xc0, v1
	s_add_i32 s12, s12, s5
	s_mul_i32 s5, s8, s23
	s_mul_hi_u32 s18, s8, s22
	s_ashr_i32 s16, s10, 6
	v_lshrrev_b32_e32 v5, 2, v4
	v_lshlrev_b32_e32 v6, 1, v4
	v_sub_u32_e32 v0, v0, v1
	s_add_i32 s5, s18, s5
	s_mul_i32 s4, s4, s22
	s_ashr_i32 s11, s10, 8
	s_lshl_b64 s[6:7], s[20:21], 8
	s_lshl_b32 s37, s16, 10
	v_and_b32_e32 v5, 4, v5
	v_and_b32_e32 v6, 24, v6
	v_lshlrev_b32_e32 v3, 5, v3
	v_ashrrev_i16_sdwa v0, v221, sext(v0) dst_sel:DWORD dst_unused:UNUSED_PAD src0_sel:DWORD src1_sel:BYTE_0
	s_add_i32 s5, s5, s4
	s_mul_i32 s4, s8, s22
	v_or3_b32 v2, v2, v5, v6
	v_and_b32_e32 v15, 32, v3
	v_bfe_i32 v16, v0, 0, 16
	s_add_u32 s30, s35, s4
	v_mul_lo_u32 v2, v2, s20
	v_add_u32_e32 v0, v15, v16
	s_addc_u32 s31, s36, s5
	s_add_i32 s38, s37, 0
	v_add_lshl_u32 v176, v2, v0, 1
	s_add_i32 m0, s38, 0x10000
	s_mul_i32 s13, s8, s95
	global_load_lds_dwordx4 v176, s[30:31]
	s_add_i32 m0, s38, 0x12000
	s_add_u32 s4, s30, s6
	global_load_lds_dwordx4 v156, s[30:31]
	s_addc_u32 s5, s31, s7
	s_add_i32 m0, s38, 0x14000
	v_mul_lo_u32 v17, v4, s20
	global_load_lds_dwordx4 v176, s[4:5]
	s_add_i32 m0, s38, 0x16000
	s_add_u32 s28, s33, s13
	v_mov_b32_e32 v157, v177
	s_addc_u32 s29, s34, s12
	s_add_i32 s39, s38, 0x2000
	v_add_lshl_u32 v160, v0, v17, 1
	v_lshl_add_u64 v[4:5], s[4:5], 0, v[176:177]
	v_lshl_add_u64 v[6:7], s[4:5], 0, v[156:157]
	global_load_lds_dwordx4 v156, s[4:5]
	s_mov_b32 m0, s38
	s_add_u32 s4, s28, s6
	global_load_lds_dwordx4 v160, s[28:29]
	s_mov_b32 m0, s39
	s_addc_u32 s5, s29, s7
	s_add_i32 s48, s38, 0x4000
	global_load_lds_dwordx4 v158, s[28:29]
	s_mov_b32 m0, s48
	s_add_i32 s49, s38, 0x6000
	global_load_lds_dwordx4 v160, s[4:5]
	s_mov_b32 m0, s49
	v_mov_b32_e32 v161, v177
	global_load_lds_dwordx4 v158, s[4:5]
	v_mov_b32_e32 v159, v177
	s_cmp_eq_u32 s11, 1
	v_lshl_add_u64 v[0:1], s[30:31], 0, v[176:177]
	v_lshl_add_u64 v[2:3], s[30:31], 0, v[156:157]
	v_lshl_add_u64 v[8:9], s[28:29], 0, v[160:161]
	v_lshl_add_u64 v[10:11], s[28:29], 0, v[158:159]
	s_cselect_b64 s[12:13], -1, 0
	s_cmp_lg_u32 s11, 1
	s_cbranch_scc1 .LBB0_460
	s_barrier

.Lxi_3:
	s_and_saveexec_b64 s[8:9], vcc
	s_cbranch_execz .LBB0_139
	s_bcnt1_i32_b64 s4, s[6:7]
	v_mov_b32_e32 v0, s4
	v_readlane_b32 s4, v254, 28
	v_readlane_b32 s5, v254, 29
	s_nop 4
	global_atomic_add v177, v0, s[4:5]
	s_branch .LBB0_139

.Lxw_9:
.LBB0_551:
	s_or_b64 exec, exec, s[0:1]
	s_mov_b64 s[0:1], 1
	v_writelane_b32 v253, s0, 54
	s_mov_b64 s[40:41], 0
	s_waitcnt lgkmcnt(0)
	v_writelane_b32 v253, s1, 55
	s_barrier
	v_readlane_b32 s0, v253, 52
	v_readlane_b32 s1, v253, 53
	s_and_b64 vcc, exec, s[0:1]
	s_cbranch_vccnz .LBB0_1299

.LBB0_743:
	s_mov_b64 s[8:9], exec
	v_mbcnt_lo_u32_b32 v1, s8, 0
	v_mbcnt_hi_u32_b32 v1, s9, v1
	v_cmp_eq_u32_e32 vcc, 0, v1
	s_and_saveexec_b64 s[6:7], vcc
	s_cbranch_execz .LBB0_745
	s_bcnt1_i32_b64 s4, s[8:9]
	v_readlane_b32 s8, v254, 26
	v_mov_b32_e32 v3, s4
	v_readlane_b32 s9, v254, 27
	s_nop 4
	global_atomic_add v3, v181, v3, s[8:9] sc0
	s_cmp_lg_u32 s101, 0
	s_cbranch_scc0 .Lea_4
	buffer_inv sc1
.Lea_4:
.LBB0_745:
	s_or_b64 exec, exec, s[6:7]
	v_cvt_f32_u32_e32 v4, v2
	s_waitcnt vmcnt(0)
	v_readfirstlane_b32 s4, v3
	v_sub_u32_e32 v3, 0, v2
	v_rcp_iflag_f32_e32 v4, v4
	v_add_u32_e32 v5, s4, v1
	v_mul_f32_e32 v4, 0x4f7ffffe, v4
	v_cvt_u32_f32_e32 v4, v4
	v_mul_lo_u32 v1, v3, v4
	v_mul_hi_u32 v1, v4, v1
	v_add_u32_e32 v1, v4, v1
	v_mul_hi_u32 v1, v5, v1
	v_mul_lo_u32 v3, v1, v2
	v_sub_u32_e32 v3, v5, v3
	v_add_u32_e32 v4, 1, v1
	v_cmp_ge_u32_e32 vcc, v3, v2
	s_nop 1
	v_cndmask_b32_e32 v1, v1, v4, vcc
	v_sub_u32_e32 v4, v3, v2
	v_cndmask_b32_e32 v3, v3, v4, vcc
	v_add_u32_e32 v4, 1, v1
	v_cmp_ge_u32_e32 vcc, v3, v2
	v_add_u32_e32 v3, 1, v5
	s_nop 0
	v_cndmask_b32_e32 v1, v1, v4, vcc
	v_mul_lo_u32 v4, v2, v1
	v_add_u32_e32 v2, v4, v2
	v_cmp_ne_u32_e32 vcc, v3, v2
	s_and_saveexec_b64 s[6:7], vcc
	s_xor_b64 s[6:7], exec, s[6:7]
	s_cbranch_execz .LBB0_759
	v_readlane_b32 s8, v254, 28
	v_readlane_b32 s9, v254, 29
	s_waitcnt lgkmcnt(0)
	s_nop 3
	global_load_dword v0, v181, s[8:9] sc1
	s_waitcnt vmcnt(0)
	v_cmp_eq_u32_e32 vcc, v0, v1
	s_and_saveexec_b64 s[8:9], vcc
	s_cbranch_execz .LBB0_758
	s_mov_b32 s4, 1
	s_mov_b64 s[10:11], 0
	s_branch .LBB0_749

.Lei_4:
.LBB0_759:
	s_andn2_saveexec_b64 s[6:7], s[6:7]
	s_cbranch_execz .LBB0_779
	s_mov_b64 s[6:7], exec
	s_cmp_lg_u32 s101, 0
	s_cbranch_scc1 .Lxl_4
	buffer_wbl2 sc1
	s_waitcnt lgkmcnt(0)
	s_waitcnt vmcnt(0)
	v_mbcnt_lo_u32_b32 v1, s6, 0
	v_mbcnt_hi_u32_b32 v1, s7, v1
	v_cmp_eq_u32_e32 vcc, 0, v1
	s_and_saveexec_b64 s[8:9], vcc
	s_cbranch_execz .LBB0_762
	s_bcnt1_i32_b64 s4, s[6:7]
	v_readlane_b32 s6, v254, 30
	v_mov_b32_e32 v2, s4
	v_readlane_b32 s7, v254, 31
	s_nop 4
	global_atomic_add v2, v181, v2, s[6:7] sc0

.Lxi_4:
	s_and_saveexec_b64 s[8:9], vcc
	s_cbranch_execz .LBB0_778
	s_bcnt1_i32_b64 s4, s[6:7]
	v_readlane_b32 s6, v254, 28
	v_mov_b32_e32 v0, s4
	v_readlane_b32 s7, v254, 29
	s_nop 4
	global_atomic_add v181, v0, s[6:7]

.Lxw_4:
.LBB0_779:
	s_or_b64 exec, exec, s[0:1]
	s_andn2_b64 vcc, exec, s[40:41]
	s_waitcnt lgkmcnt(0)
	s_barrier
	s_cbranch_vccnz .LBB0_830
	v_readlane_b32 s16, v253, 32
	v_readlane_b32 s18, v253, 34
	v_readlane_b32 s19, v253, 35
	v_readlane_b32 s20, v253, 36
	v_readlane_b32 s30, v253, 46
	v_readlane_b32 s31, v253, 47
	v_readlane_b32 s0, v255, 20
	s_mov_b64 s[18:19], s[30:31]
	s_movk_i32 s20, 0x100
	v_mov_b32_e32 v12, v218
	v_readlane_b32 s1, v255, 21
	s_and_b64 vcc, exec, s[0:1]
	v_readfirstlane_b32 s10, v12
	v_readlane_b32 s17, v253, 33
	v_readlane_b32 s21, v253, 37
	v_readlane_b32 s22, v253, 38
	v_readlane_b32 s23, v253, 39
	v_readlane_b32 s24, v253, 40
	v_readlane_b32 s25, v253, 41
	v_readlane_b32 s26, v253, 42
	v_readlane_b32 s27, v253, 43
	v_readlane_b32 s28, v253, 44
	v_readlane_b32 s29, v253, 45
	s_cbranch_vccnz .LBB0_805
	v_lshlrev_b32_e32 v0, 4, v12
	v_add_u32_e32 v1, 0x2000, v0
	v_ashrrev_i32_e32 v2, 31, v1
	v_lshrrev_b32_e32 v2, 22, v2
	v_add_u32_e32 v2, v1, v2
	v_ashrrev_i32_e32 v2, 10, v2
	v_mul_i32_i24_e32 v3, 0x400, v2
	v_sub_u32_e32 v1, v1, v3
	v_lshrrev_b32_e32 v3, 4, v1
	v_bitop3_b32 v1, v3, v1, 32 bitop3:0x6c
	v_ashrrev_i32_e32 v3, 31, v1
	v_lshrrev_b32_e32 v3, 26, v3
	v_add_u32_e32 v3, v1, v3
	v_lshlrev_b32_e32 v5, 3, v2
	v_ashrrev_i32_e32 v4, 6, v3
	v_and_b32_e32 v5, -16, v5
	v_lshlrev_b32_e32 v2, 5, v2
	v_add_u32_e32 v5, v4, v5
	v_and_b32_e32 v13, 32, v2
	v_and_b32_e32 v2, 0xc0, v3
	v_and_b32_e32 v4, 3, v4
	s_mov_b32 s8, 0x7fffffe0
	v_lshrrev_b32_e32 v6, 2, v5
	v_lshlrev_b32_e32 v7, 1, v5
	v_sub_u32_e32 v1, v1, v2
	v_and_or_b32 v4, v5, s8, v4
	v_and_b32_e32 v6, 4, v6
	v_and_b32_e32 v7, 24, v7
	v_ashrrev_i16_sdwa v1, v205, sext(v1) dst_sel:DWORD dst_unused:UNUSED_PAD src0_sel:DWORD src1_sel:BYTE_0
	v_or3_b32 v4, v4, v6, v7
	v_bfe_i32 v14, v1, 0, 16
	v_mul_lo_u32 v4, v4, s20
	v_add_u32_e32 v1, v13, v14
	v_mul_lo_u32 v15, v5, s20
	v_add_lshl_u32 v128, v4, v1, 1
	v_add_lshl_u32 v130, v1, v15, 1
	v_bfe_i32 v1, v12, 27, 1
	v_lshrrev_b32_e32 v1, 22, v1
	v_add_u32_e32 v1, v0, v1
	v_and_b32_e32 v1, 0xfffffc00, v1
	v_sub_u32_e32 v0, v0, v1
	v_lshrrev_b32_e32 v1, 4, v0
	v_ashrrev_i32_e32 v3, 31, v12
	v_bitop3_b32 v0, v1, v0, 32 bitop3:0x6c
	v_lshrrev_b32_e32 v3, 26, v3
	v_ashrrev_i32_e32 v1, 31, v0
	v_add_u32_e32 v3, v12, v3
	s_add_u32 s4, s18, 0x13900000
	v_lshrrev_b32_e32 v1, 26, v1
	v_ashrrev_i32_e32 v3, 6, v3
	s_addc_u32 s33, s19, 0
	s_and_b32 s98, s2, 7
	s_mul_i32 s98, s98, 0x1400000
	s_add_u32 s4, s4, s98
	s_addc_u32 s33, s33, 0
	v_add_u32_e32 v1, v0, v1
	v_lshlrev_b32_e32 v4, 3, v3
	s_add_u32 s34, s18, 0x7f00000
	v_ashrrev_i32_e32 v2, 6, v1
	v_and_b32_e32 v4, -16, v4
	s_addc_u32 s35, s19, 0
	s_ashr_i32 s21, s20, 31
	v_add_u32_e32 v4, v2, v4
	v_and_b32_e32 v2, 3, v2
	s_lshl_b64 s[6:7], s[20:21], 9
	v_and_or_b32 v2, v4, s8, v2
	v_readlane_b32 s8, v254, 53
	s_mul_i32 s8, s6, s8
	s_mul_hi_u32 s9, s6, s95
	s_add_i32 s14, s9, s8
	s_lshr_b64 s[8:9], s[20:21], 23
	v_readlane_b32 s24, v254, 50
	s_mul_i32 s9, s8, s95
	v_readlane_b32 s25, v254, 51
	v_and_b32_e32 v1, 0xc0, v1
	s_add_i32 s14, s14, s9
	s_mul_i32 s9, s6, s25
	s_mul_hi_u32 s16, s6, s24
	s_ashr_i32 s11, s10, 6
	v_lshrrev_b32_e32 v5, 2, v4
	v_lshlrev_b32_e32 v6, 1, v4
	v_sub_u32_e32 v0, v0, v1
	s_add_i32 s9, s16, s9
	s_mul_i32 s8, s8, s24
	s_ashr_i32 s22, s10, 8
	s_lshl_b64 s[0:1], s[20:21], 8
	s_lshl_b32 s36, s11, 10
	v_and_b32_e32 v5, 4, v5
	v_and_b32_e32 v6, 24, v6
	v_lshlrev_b32_e32 v3, 5, v3
	v_ashrrev_i16_sdwa v0, v205, sext(v0) dst_sel:DWORD dst_unused:UNUSED_PAD src0_sel:DWORD src1_sel:BYTE_0
	s_add_i32 s9, s9, s8
	s_mul_i32 s8, s6, s24
	v_or3_b32 v2, v2, v5, v6
	v_and_b32_e32 v16, 32, v3
	v_bfe_i32 v17, v0, 0, 16
	s_add_u32 s30, s34, s8
	v_mul_lo_u32 v2, v2, s20
	v_add_u32_e32 v0, v16, v17
	s_addc_u32 s31, s35, s9
	s_add_i32 s37, s36, 0
	v_add_lshl_u32 v132, v2, v0, 1
	s_add_i32 m0, s37, 0x10000
	s_mul_i32 s15, s6, s95
	global_load_lds_dwordx4 v132, s[30:31]
	s_add_i32 m0, s37, 0x12000
	s_add_u32 s8, s30, s0
	global_load_lds_dwordx4 v128, s[30:31]
	s_addc_u32 s9, s31, s1
	s_add_i32 m0, s37, 0x14000
	v_mul_lo_u32 v18, v4, s20
	global_load_lds_dwordx4 v132, s[8:9]
	s_add_i32 m0, s37, 0x16000
	s_add_u32 s16, s4, s15
	v_mov_b32_e32 v133, v181
	v_mov_b32_e32 v129, v181
	s_addc_u32 s17, s33, s14
	s_add_i32 s38, s37, 0x2000
	v_add_lshl_u32 v134, v0, v18, 1
	v_lshl_add_u64 v[4:5], s[8:9], 0, v[132:133]
	v_lshl_add_u64 v[6:7], s[8:9], 0, v[128:129]
	global_load_lds_dwordx4 v128, s[8:9]
	s_mov_b32 m0, s37
	s_add_u32 s8, s16, s0
	global_load_lds_dwordx4 v134, s[16:17]
	s_mov_b32 m0, s38
	s_addc_u32 s9, s17, s1
	s_add_i32 s39, s37, 0x4000
	global_load_lds_dwordx4 v130, s[16:17]
	s_mov_b32 m0, s39
	s_add_i32 s44, s37, 0x6000
	global_load_lds_dwordx4 v134, s[8:9]
	s_mov_b32 m0, s44
	v_mov_b32_e32 v135, v181
	global_load_lds_dwordx4 v130, s[8:9]
	v_mov_b32_e32 v131, v181
	s_cmp_eq_u32 s22, 1
	v_lshl_add_u64 v[0:1], s[30:31], 0, v[132:133]
	v_lshl_add_u64 v[2:3], s[30:31], 0, v[128:129]
	v_lshl_add_u64 v[8:9], s[16:17], 0, v[134:135]
	v_lshl_add_u64 v[10:11], s[16:17], 0, v[130:131]
	s_cselect_b64 s[8:9], -1, 0
	s_cmp_lg_u32 s22, 1
	s_cbranch_scc1 .LBB0_783
	s_barrier

.Lxw_5:
.LBB0_935:
	s_or_b64 exec, exec, s[0:1]
	v_readlane_b32 s16, v253, 32
	v_readlane_b32 s0, v254, 42
	v_readlane_b32 s30, v253, 46
	v_readlane_b32 s31, v253, 47
	v_readlane_b32 s1, v254, 43
	s_mov_b64 s[6:7], s[30:31]
	s_andn2_b64 vcc, exec, s[0:1]
	s_waitcnt lgkmcnt(0)
	s_barrier
	v_readlane_b32 s17, v253, 33
	v_readlane_b32 s18, v253, 34
	v_readlane_b32 s19, v253, 35
	v_readlane_b32 s20, v253, 36
	v_readlane_b32 s21, v253, 37
	v_readlane_b32 s22, v253, 38
	v_readlane_b32 s23, v253, 39
	v_readlane_b32 s24, v253, 40
	v_readlane_b32 s25, v253, 41
	v_readlane_b32 s26, v253, 42
	v_readlane_b32 s27, v253, 43
	v_readlane_b32 s28, v253, 44
	v_readlane_b32 s29, v253, 45
	s_cbranch_vccnz .LBB0_983
	s_add_u32 s8, s6, 0x12d00000
	s_addc_u32 s9, s7, 0
	s_and_b32 s98, s2, 7
	s_mul_i32 s98, s98, 0xa00000
	s_add_u32 s8, s8, s98
	s_addc_u32 s9, s9, 0
	s_add_u32 s4, s6, 0xa900000
	s_addc_u32 s33, s7, 0
	s_add_u32 s44, s6, 0x12900000
	s_addc_u32 s45, s7, 0
	s_add_u32 s46, s6, 0xe900000
	s_addc_u32 s47, s7, 0
	s_add_u32 s14, s6, 0x13900000
	s_addc_u32 s15, s7, 0
	s_and_b32 s98, s2, 7
	s_mul_i32 s98, s98, 0xe00000
	s_add_u32 s14, s14, s98
	s_addc_u32 s15, s15, 0
	v_readlane_b32 s48, v255, 10
	s_and_b32 s100, s2, 7
	s_lshl_b32 s100, s100, 5
	s_add_i32 s48, s48, s100
	s_add_i32 s100, s48, 64
	s_branch .LBB0_938

.Lxw_6:
.LBB0_1035:
	s_or_b64 exec, exec, s[0:1]
	v_readlane_b32 s16, v253, 32
	v_readlane_b32 s30, v253, 46
	v_readlane_b32 s31, v253, 47
	v_readlane_b32 s6, v255, 20
	s_mov_b64 s[0:1], s[30:31]
	s_movk_i32 s16, 0x400
	v_mov_b32_e32 v18, v218
	v_readlane_b32 s7, v255, 21
	s_waitcnt lgkmcnt(0)
	s_barrier
	s_and_b64 vcc, exec, s[6:7]
	v_readfirstlane_b32 s10, v18
	v_readlane_b32 s17, v253, 33
	v_readlane_b32 s18, v253, 34
	v_readlane_b32 s19, v253, 35
	v_readlane_b32 s20, v253, 36
	v_readlane_b32 s21, v253, 37
	v_readlane_b32 s22, v253, 38
	v_readlane_b32 s23, v253, 39
	v_readlane_b32 s24, v253, 40
	v_readlane_b32 s25, v253, 41
	v_readlane_b32 s26, v253, 42
	v_readlane_b32 s27, v253, 43
	v_readlane_b32 s28, v253, 44
	v_readlane_b32 s29, v253, 45
	s_cbranch_vccnz .LBB0_1076
	v_lshlrev_b32_e32 v0, 4, v18
	v_add_u32_e32 v1, 0x2000, v0
	v_ashrrev_i32_e32 v2, 31, v1
	v_lshrrev_b32_e32 v2, 22, v2
	v_add_u32_e32 v2, v1, v2
	v_ashrrev_i32_e32 v2, 10, v2
	v_mul_i32_i24_e32 v3, 0x400, v2
	v_sub_u32_e32 v1, v1, v3
	v_lshrrev_b32_e32 v3, 4, v1
	v_bitop3_b32 v1, v3, v1, 32 bitop3:0x6c
	v_ashrrev_i32_e32 v3, 31, v1
	v_lshrrev_b32_e32 v3, 26, v3
	v_add_u32_e32 v3, v1, v3
	v_lshlrev_b32_e32 v5, 3, v2
	v_ashrrev_i32_e32 v4, 6, v3
	v_and_b32_e32 v5, -16, v5
	v_lshlrev_b32_e32 v2, 5, v2
	v_add_u32_e32 v5, v4, v5
	v_and_b32_e32 v12, 32, v2
	v_and_b32_e32 v2, 0xc0, v3
	v_and_b32_e32 v4, 3, v4
	s_mov_b32 s14, 0x7fffffe0
	v_lshrrev_b32_e32 v6, 2, v5
	v_lshlrev_b32_e32 v7, 1, v5
	v_sub_u32_e32 v1, v1, v2
	v_and_or_b32 v4, v5, s14, v4
	v_and_b32_e32 v6, 4, v6
	v_and_b32_e32 v7, 24, v7
	v_ashrrev_i16_sdwa v1, v205, sext(v1) dst_sel:DWORD dst_unused:UNUSED_PAD src0_sel:DWORD src1_sel:BYTE_0
	v_or3_b32 v4, v4, v6, v7
	v_bfe_i32 v13, v1, 0, 16
	v_mul_lo_u32 v4, v4, s16
	v_add_u32_e32 v1, v12, v13
	v_mul_lo_u32 v14, v5, s16
	v_add_lshl_u32 v156, v4, v1, 1
	v_add_lshl_u32 v158, v1, v14, 1
	v_bfe_i32 v1, v18, 27, 1
	v_lshrrev_b32_e32 v1, 22, v1
	v_add_u32_e32 v1, v0, v1
	v_and_b32_e32 v1, 0xfffffc00, v1
	v_sub_u32_e32 v0, v0, v1
	v_readlane_b32 s6, v253, 54
	v_lshrrev_b32_e32 v1, 4, v0
	v_ashrrev_i32_e32 v3, 31, v18
	s_add_u32 s4, s0, 0x13900000
	v_readlane_b32 s7, v253, 55
	v_bitop3_b32 v0, v1, v0, 32 bitop3:0x6c
	v_lshrrev_b32_e32 v3, 26, v3
	s_addc_u32 s33, s1, 0
	s_and_b32 s98, s2, 7
	s_mul_i32 s98, s98, 0xe00000
	s_add_u32 s4, s4, s98
	s_addc_u32 s33, s33, 0
	s_lshl_b64 s[6:7], s[6:7], 21
	v_ashrrev_i32_e32 v1, 31, v0
	v_add_u32_e32 v3, v18, v3
	s_add_u32 s6, s0, s6
	v_lshrrev_b32_e32 v1, 26, v1
	v_ashrrev_i32_e32 v3, 6, v3
	s_addc_u32 s7, s1, s7
	v_add_u32_e32 v1, v0, v1
	v_lshlrev_b32_e32 v4, 3, v3
	s_add_u32 s34, s6, 0x8340000
	v_ashrrev_i32_e32 v2, 6, v1
	v_and_b32_e32 v4, -16, v4
	s_addc_u32 s35, s7, 0
	s_ashr_i32 s17, s16, 31
	v_add_u32_e32 v4, v2, v4
	v_and_b32_e32 v2, 3, v2
	s_lshl_b64 s[8:9], s[16:17], 9
	v_and_or_b32 v2, v4, s14, v2
	v_readlane_b32 s14, v254, 53
	s_mul_i32 s14, s8, s14
	s_mul_hi_u32 s15, s8, s95
	s_add_i32 s18, s15, s14
	s_lshr_b64 s[14:15], s[16:17], 23
	v_readlane_b32 s22, v254, 50
	s_mul_i32 s15, s14, s95
	v_readlane_b32 s23, v254, 51
	v_and_b32_e32 v1, 0xc0, v1
	s_add_i32 s18, s18, s15
	s_mul_i32 s15, s8, s23
	s_mul_hi_u32 s21, s8, s22
	s_ashr_i32 s20, s10, 6
	v_lshrrev_b32_e32 v5, 2, v4
	v_lshlrev_b32_e32 v6, 1, v4
	v_sub_u32_e32 v0, v0, v1
	s_add_i32 s15, s21, s15
	s_mul_i32 s14, s14, s22
	s_ashr_i32 s11, s10, 8
	s_lshl_b64 s[6:7], s[16:17], 8
	s_lshl_b32 s36, s20, 10
	v_and_b32_e32 v5, 4, v5
	v_and_b32_e32 v6, 24, v6
	v_lshlrev_b32_e32 v3, 5, v3
	v_ashrrev_i16_sdwa v0, v205, sext(v0) dst_sel:DWORD dst_unused:UNUSED_PAD src0_sel:DWORD src1_sel:BYTE_0
	s_add_i32 s15, s15, s14
	s_mul_i32 s14, s8, s22
	v_or3_b32 v2, v2, v5, v6
	v_and_b32_e32 v15, 32, v3
	v_bfe_i32 v16, v0, 0, 16
	s_add_u32 s30, s34, s14
	v_mul_lo_u32 v2, v2, s16
	v_add_u32_e32 v0, v15, v16
	s_addc_u32 s31, s35, s15
	s_add_i32 s37, s36, 0
	v_add_lshl_u32 v180, v2, v0, 1
	s_add_i32 m0, s37, 0x10000
	s_mul_i32 s19, s8, s95
	global_load_lds_dwordx4 v180, s[30:31]
	s_add_i32 m0, s37, 0x12000
	s_add_u32 s14, s30, s6
	global_load_lds_dwordx4 v156, s[30:31]
	s_addc_u32 s15, s31, s7
	s_add_i32 m0, s37, 0x14000
	v_mul_lo_u32 v17, v4, s16
	global_load_lds_dwordx4 v180, s[14:15]
	s_add_i32 m0, s37, 0x16000
	s_add_u32 s28, s4, s19
	v_mov_b32_e32 v157, v181
	s_addc_u32 s29, s33, s18
	s_add_i32 s38, s37, 0x2000
	s_waitcnt vmcnt(0)
	v_add_lshl_u32 v160, v0, v17, 1
	v_lshl_add_u64 v[4:5], s[14:15], 0, v[180:181]
	v_lshl_add_u64 v[6:7], s[14:15], 0, v[156:157]
	global_load_lds_dwordx4 v156, s[14:15]
	s_mov_b32 m0, s37
	s_add_u32 s14, s28, s6
	global_load_lds_dwordx4 v160, s[28:29]
	s_mov_b32 m0, s38
	s_addc_u32 s15, s29, s7
	s_add_i32 s39, s37, 0x4000
	global_load_lds_dwordx4 v158, s[28:29]
	s_mov_b32 m0, s39
	s_add_i32 s46, s37, 0x6000
	global_load_lds_dwordx4 v160, s[14:15]
	s_mov_b32 m0, s46
	v_mov_b32_e32 v161, v181
	global_load_lds_dwordx4 v158, s[14:15]
	v_mov_b32_e32 v159, v181
	s_cmp_eq_u32 s11, 1
	v_mov_b32_e32 v240, 1
	v_lshl_add_u64 v[0:1], s[30:31], 0, v[180:181]
	v_lshl_add_u64 v[2:3], s[30:31], 0, v[156:157]
	v_lshl_add_u64 v[8:9], s[28:29], 0, v[160:161]
	v_lshl_add_u64 v[10:11], s[28:29], 0, v[158:159]
	s_cselect_b64 s[14:15], -1, 0
	s_cmp_lg_u32 s11, 1
	s_cbranch_scc1 .LBB0_1038
	s_barrier

.Lxw_7:
.LBB0_1128:
	s_or_b64 exec, exec, s[0:1]
	v_readlane_b32 s16, v253, 32
	v_readlane_b32 s30, v253, 46
	v_readlane_b32 s31, v253, 47
	v_readlane_b32 s6, v254, 36
	s_mov_b64 s[0:1], s[30:31]
	s_movk_i32 s16, 0x400
	v_mov_b32_e32 v12, v218
	v_readlane_b32 s7, v254, 37
	s_waitcnt lgkmcnt(0)
	s_barrier
	s_andn2_b64 vcc, exec, s[6:7]
	v_readfirstlane_b32 s10, v12
	v_readlane_b32 s17, v253, 33
	v_readlane_b32 s18, v253, 34
	v_readlane_b32 s19, v253, 35
	v_readlane_b32 s20, v253, 36
	v_readlane_b32 s21, v253, 37
	v_readlane_b32 s22, v253, 38
	v_readlane_b32 s23, v253, 39
	v_readlane_b32 s24, v253, 40
	v_readlane_b32 s25, v253, 41
	v_readlane_b32 s26, v253, 42
	v_readlane_b32 s27, v253, 43
	v_readlane_b32 s28, v253, 44
	v_readlane_b32 s29, v253, 45
	s_cbranch_vccnz .LBB0_1154
	v_lshlrev_b32_e32 v0, 4, v12
	v_add_u32_e32 v1, 0x2000, v0
	v_ashrrev_i32_e32 v2, 31, v1
	v_lshrrev_b32_e32 v2, 22, v2
	v_add_u32_e32 v2, v1, v2
	v_ashrrev_i32_e32 v2, 10, v2
	v_mul_i32_i24_e32 v3, 0x400, v2
	v_sub_u32_e32 v1, v1, v3
	v_lshrrev_b32_e32 v3, 4, v1
	v_bitop3_b32 v1, v3, v1, 32 bitop3:0x6c
	v_ashrrev_i32_e32 v3, 31, v1
	v_lshrrev_b32_e32 v3, 26, v3
	v_add_u32_e32 v3, v1, v3
	v_lshlrev_b32_e32 v5, 3, v2
	v_ashrrev_i32_e32 v4, 6, v3
	v_and_b32_e32 v5, -16, v5
	v_lshlrev_b32_e32 v2, 5, v2
	v_add_u32_e32 v5, v4, v5
	v_and_b32_e32 v13, 32, v2
	v_and_b32_e32 v2, 0xc0, v3
	v_and_b32_e32 v4, 3, v4
	s_mov_b32 s14, 0x7fffffe0
	v_lshrrev_b32_e32 v6, 2, v5
	v_lshlrev_b32_e32 v7, 1, v5
	v_sub_u32_e32 v1, v1, v2
	v_and_or_b32 v4, v5, s14, v4
	v_and_b32_e32 v6, 4, v6
	v_and_b32_e32 v7, 24, v7
	v_ashrrev_i16_sdwa v1, v205, sext(v1) dst_sel:DWORD dst_unused:UNUSED_PAD src0_sel:DWORD src1_sel:BYTE_0
	v_or3_b32 v4, v4, v6, v7
	v_bfe_i32 v14, v1, 0, 16
	v_mul_lo_u32 v4, v4, s16
	v_add_u32_e32 v1, v13, v14
	v_mul_lo_u32 v15, v5, s16
	v_add_lshl_u32 v132, v4, v1, 1
	v_add_lshl_u32 v134, v1, v15, 1
	v_bfe_i32 v1, v12, 27, 1
	v_lshrrev_b32_e32 v1, 22, v1
	v_add_u32_e32 v1, v0, v1
	v_and_b32_e32 v1, 0xfffffc00, v1
	v_sub_u32_e32 v0, v0, v1
	v_lshrrev_b32_e32 v1, 4, v0
	v_ashrrev_i32_e32 v3, 31, v12
	s_add_u32 s4, s0, 0xc00000
	v_readlane_b32 s6, v253, 54
	v_bitop3_b32 v0, v1, v0, 32 bitop3:0x6c
	v_lshrrev_b32_e32 v3, 26, v3
	s_addc_u32 s33, s1, 0
	s_mul_i32 s6, s6, 0xb00000
	v_ashrrev_i32_e32 v1, 31, v0
	v_add_u32_e32 v3, v12, v3
	v_readlane_b32 s7, v253, 55
	s_add_u32 s6, s0, s6
	v_lshrrev_b32_e32 v1, 26, v1
	v_ashrrev_i32_e32 v3, 6, v3
	s_addc_u32 s7, s1, 0
	v_add_u32_e32 v1, v0, v1
	v_lshlrev_b32_e32 v4, 3, v3
	s_add_u32 s34, s6, 0x8740000
	v_ashrrev_i32_e32 v2, 6, v1
	v_and_b32_e32 v4, -16, v4
	s_addc_u32 s35, s7, 0
	s_ashr_i32 s17, s16, 31
	v_add_u32_e32 v4, v2, v4
	v_and_b32_e32 v2, 3, v2
	s_lshl_b64 s[8:9], s[16:17], 9
	v_and_or_b32 v2, v4, s14, v2
	v_readlane_b32 s14, v254, 52
	v_readlane_b32 s19, v255, 6
	s_mul_i32 s14, s8, s14
	s_mul_hi_u32 s15, s8, s19
	s_add_i32 s18, s15, s14
	s_lshr_b64 s[14:15], s[16:17], 23
	v_readlane_b32 s22, v254, 47
	s_mul_i32 s15, s14, s19
	v_readlane_b32 s23, v254, 48
	v_and_b32_e32 v1, 0xc0, v1
	s_add_i32 s18, s18, s15
	s_mul_i32 s15, s8, s23
	s_mul_hi_u32 s21, s8, s22
	s_ashr_i32 s20, s10, 6
	v_lshrrev_b32_e32 v5, 2, v4
	v_lshlrev_b32_e32 v6, 1, v4
	v_sub_u32_e32 v0, v0, v1
	s_add_i32 s15, s21, s15
	s_mul_i32 s14, s14, s22
	s_ashr_i32 s11, s10, 8
	s_lshl_b64 s[6:7], s[16:17], 8
	s_lshl_b32 s36, s20, 10
	v_and_b32_e32 v5, 4, v5
	v_and_b32_e32 v6, 24, v6
	v_lshlrev_b32_e32 v3, 5, v3
	v_ashrrev_i16_sdwa v0, v205, sext(v0) dst_sel:DWORD dst_unused:UNUSED_PAD src0_sel:DWORD src1_sel:BYTE_0
	s_add_i32 s15, s15, s14
	s_mul_i32 s14, s8, s22
	v_or3_b32 v2, v2, v5, v6
	v_and_b32_e32 v16, 32, v3
	v_bfe_i32 v17, v0, 0, 16
	s_add_u32 s30, s34, s14
	v_mul_lo_u32 v2, v2, s16
	v_add_u32_e32 v0, v16, v17
	s_addc_u32 s31, s35, s15
	s_add_i32 s37, s36, 0
	v_add_lshl_u32 v180, v2, v0, 1
	s_add_i32 m0, s37, 0x10000
	s_mul_i32 s19, s8, s19
	global_load_lds_dwordx4 v180, s[30:31]
	s_add_i32 m0, s37, 0x12000
	s_add_u32 s14, s30, s6
	global_load_lds_dwordx4 v132, s[30:31]
	s_addc_u32 s15, s31, s7
	s_add_i32 m0, s37, 0x14000
	v_mul_lo_u32 v18, v4, s16
	global_load_lds_dwordx4 v180, s[14:15]
	s_add_i32 m0, s37, 0x16000
	s_add_u32 s28, s4, s19
	v_mov_b32_e32 v133, v181
	s_addc_u32 s29, s33, s18
	s_add_i32 s38, s37, 0x2000
	v_add_lshl_u32 v136, v0, v18, 1
	v_lshl_add_u64 v[4:5], s[14:15], 0, v[180:181]
	v_lshl_add_u64 v[6:7], s[14:15], 0, v[132:133]
	global_load_lds_dwordx4 v132, s[14:15]
	s_mov_b32 m0, s37
	s_add_u32 s14, s28, s6
	global_load_lds_dwordx4 v136, s[28:29]
	s_mov_b32 m0, s38
	s_addc_u32 s15, s29, s7
	s_add_i32 s39, s37, 0x4000
	global_load_lds_dwordx4 v134, s[28:29]
	s_mov_b32 m0, s39
	s_add_i32 s46, s37, 0x6000
	global_load_lds_dwordx4 v136, s[14:15]
	s_mov_b32 m0, s46
	v_mov_b32_e32 v137, v181
	global_load_lds_dwordx4 v134, s[14:15]
	v_mov_b32_e32 v135, v181
	s_cmp_eq_u32 s11, 1
	v_lshl_add_u64 v[0:1], s[30:31], 0, v[180:181]
	v_lshl_add_u64 v[2:3], s[30:31], 0, v[132:133]
	v_lshl_add_u64 v[8:9], s[28:29], 0, v[136:137]
	v_lshl_add_u64 v[10:11], s[28:29], 0, v[134:135]
	s_cselect_b64 s[14:15], -1, 0
	s_cmp_lg_u32 s11, 1
	s_cbranch_scc1 .LBB0_1131
	s_barrier

.Lxw_8:
.LBB0_1206:
	s_or_b64 exec, exec, s[0:1]
	v_readlane_b32 s16, v253, 32
	v_readlane_b32 s18, v253, 34
	v_readlane_b32 s30, v253, 46
	v_readlane_b32 s31, v253, 47
	v_readlane_b32 s6, v255, 20
	s_mov_b64 s[0:1], s[30:31]
	s_movk_i32 s18, 0xb00
	v_mov_b32_e32 v18, v218
	v_readlane_b32 s7, v255, 21
	s_waitcnt lgkmcnt(0)
	s_barrier
	s_and_b64 vcc, exec, s[6:7]
	v_readfirstlane_b32 s10, v18
	v_readlane_b32 s17, v253, 33
	v_readlane_b32 s19, v253, 35
	v_readlane_b32 s20, v253, 36
	v_readlane_b32 s21, v253, 37
	v_readlane_b32 s22, v253, 38
	v_readlane_b32 s23, v253, 39
	v_readlane_b32 s24, v253, 40
	v_readlane_b32 s25, v253, 41
	v_readlane_b32 s26, v253, 42
	v_readlane_b32 s27, v253, 43
	v_readlane_b32 s28, v253, 44
	v_readlane_b32 s29, v253, 45
	s_cbranch_vccnz .LBB0_1248
	v_lshlrev_b32_e32 v0, 4, v18
	v_add_u32_e32 v1, 0x2000, v0
	v_ashrrev_i32_e32 v2, 31, v1
	v_lshrrev_b32_e32 v2, 22, v2
	v_add_u32_e32 v2, v1, v2
	v_ashrrev_i32_e32 v2, 10, v2
	v_mul_i32_i24_e32 v3, 0x400, v2
	v_sub_u32_e32 v1, v1, v3
	v_lshrrev_b32_e32 v3, 4, v1
	v_bitop3_b32 v1, v3, v1, 32 bitop3:0x6c
	v_ashrrev_i32_e32 v3, 31, v1
	v_lshrrev_b32_e32 v3, 26, v3
	v_add_u32_e32 v3, v1, v3
	v_lshlrev_b32_e32 v5, 3, v2
	v_ashrrev_i32_e32 v4, 6, v3
	v_and_b32_e32 v5, -16, v5
	v_lshlrev_b32_e32 v2, 5, v2
	v_add_u32_e32 v5, v4, v5
	v_and_b32_e32 v12, 32, v2
	v_and_b32_e32 v2, 0xc0, v3
	v_and_b32_e32 v4, 3, v4
	s_mov_b32 s14, 0x7fffffe0
	v_lshrrev_b32_e32 v6, 2, v5
	v_lshlrev_b32_e32 v7, 1, v5
	v_sub_u32_e32 v1, v1, v2
	v_and_or_b32 v4, v5, s14, v4
	v_and_b32_e32 v6, 4, v6
	v_and_b32_e32 v7, 24, v7
	v_ashrrev_i16_sdwa v1, v205, sext(v1) dst_sel:DWORD dst_unused:UNUSED_PAD src0_sel:DWORD src1_sel:BYTE_0
	v_or3_b32 v4, v4, v6, v7
	v_bfe_i32 v13, v1, 0, 16
	v_mul_lo_u32 v4, v4, s18
	v_add_u32_e32 v1, v12, v13
	v_mul_lo_u32 v14, v5, s18
	v_add_lshl_u32 v156, v4, v1, 1
	v_add_lshl_u32 v158, v1, v14, 1
	v_bfe_i32 v1, v18, 27, 1
	v_lshrrev_b32_e32 v1, 22, v1
	v_add_u32_e32 v1, v0, v1
	v_and_b32_e32 v1, 0xfffffc00, v1
	v_sub_u32_e32 v0, v0, v1
	v_lshrrev_b32_e32 v1, 4, v0
	v_ashrrev_i32_e32 v3, 31, v18
	s_add_u32 s4, s0, 0x12d00000
	v_readlane_b32 s6, v253, 54
	v_bitop3_b32 v0, v1, v0, 32 bitop3:0x6c
	v_lshrrev_b32_e32 v3, 26, v3
	s_addc_u32 s30, s1, 0
	s_mul_i32 s6, s6, 0x580000
	v_ashrrev_i32_e32 v1, 31, v0
	v_add_u32_e32 v3, v18, v3
	v_readlane_b32 s7, v253, 55
	s_add_u32 s6, s0, s6
	v_lshrrev_b32_e32 v1, 26, v1
	v_ashrrev_i32_e32 v3, 6, v3
	s_addc_u32 s7, s1, 0
	v_add_u32_e32 v1, v0, v1
	v_lshlrev_b32_e32 v4, 3, v3
	s_add_u32 s31, s6, 0x9d40000
	v_ashrrev_i32_e32 v2, 6, v1
	v_and_b32_e32 v4, -16, v4
	s_addc_u32 s33, s7, 0
	s_ashr_i32 s19, s18, 31
	v_add_u32_e32 v4, v2, v4
	v_and_b32_e32 v2, 3, v2
	s_lshl_b64 s[8:9], s[18:19], 9
	v_and_or_b32 v2, v4, s14, v2
	v_readlane_b32 s14, v254, 53
	s_mul_i32 s14, s8, s14
	s_mul_hi_u32 s15, s8, s95
	s_add_i32 s16, s15, s14
	s_lshr_b64 s[14:15], s[18:19], 23
	v_readlane_b32 s22, v254, 50
	s_mul_i32 s15, s14, s95
	v_readlane_b32 s23, v254, 51
	v_and_b32_e32 v1, 0xc0, v1
	s_add_i32 s16, s16, s15
	s_mul_i32 s15, s8, s23
	s_mul_hi_u32 s21, s8, s22
	s_ashr_i32 s20, s10, 6
	v_lshrrev_b32_e32 v5, 2, v4
	v_lshlrev_b32_e32 v6, 1, v4
	v_sub_u32_e32 v0, v0, v1
	s_add_i32 s15, s21, s15
	s_mul_i32 s14, s14, s22
	s_ashr_i32 s11, s10, 8
	s_lshl_b64 s[6:7], s[18:19], 8
	s_lshl_b32 s34, s20, 10
	v_and_b32_e32 v5, 4, v5
	v_and_b32_e32 v6, 24, v6
	v_lshlrev_b32_e32 v3, 5, v3
	v_ashrrev_i16_sdwa v0, v205, sext(v0) dst_sel:DWORD dst_unused:UNUSED_PAD src0_sel:DWORD src1_sel:BYTE_0
	s_add_i32 s15, s15, s14
	s_mul_i32 s14, s8, s22
	v_or3_b32 v2, v2, v5, v6
	v_and_b32_e32 v15, 32, v3
	v_bfe_i32 v16, v0, 0, 16
	s_add_u32 s28, s31, s14
	v_mul_lo_u32 v2, v2, s18
	v_add_u32_e32 v0, v15, v16
	s_addc_u32 s29, s33, s15
	s_add_i32 s35, s34, 0
	v_add_lshl_u32 v180, v2, v0, 1
	s_add_i32 m0, s35, 0x10000
	s_mul_i32 s17, s8, s95
	global_load_lds_dwordx4 v180, s[28:29]
	s_add_i32 m0, s35, 0x12000
	s_add_u32 s14, s28, s6
	global_load_lds_dwordx4 v156, s[28:29]
	s_addc_u32 s15, s29, s7
	s_add_i32 m0, s35, 0x14000
	v_mul_lo_u32 v17, v4, s18
	global_load_lds_dwordx4 v180, s[14:15]
	s_add_i32 m0, s35, 0x16000
	s_add_u32 s26, s4, s17
	v_mov_b32_e32 v157, v181
	s_addc_u32 s27, s30, s16
	s_add_i32 s36, s35, 0x2000
	s_waitcnt vmcnt(0)
	v_add_lshl_u32 v160, v0, v17, 1
	v_lshl_add_u64 v[4:5], s[14:15], 0, v[180:181]
	v_lshl_add_u64 v[6:7], s[14:15], 0, v[156:157]
	global_load_lds_dwordx4 v156, s[14:15]
	s_mov_b32 m0, s35
	s_add_u32 s14, s26, s6
	global_load_lds_dwordx4 v160, s[26:27]
	s_mov_b32 m0, s36
	s_addc_u32 s15, s27, s7
	s_add_i32 s37, s35, 0x4000
	global_load_lds_dwordx4 v158, s[26:27]
	s_mov_b32 m0, s37
	s_add_i32 s38, s35, 0x6000
	global_load_lds_dwordx4 v160, s[14:15]
	s_mov_b32 m0, s38
	v_mov_b32_e32 v161, v181
	global_load_lds_dwordx4 v158, s[14:15]
	v_mov_b32_e32 v159, v181
	s_cmp_eq_u32 s11, 1
	v_mov_b32_e32 v240, 1
	v_lshl_add_u64 v[0:1], s[28:29], 0, v[180:181]
	v_lshl_add_u64 v[2:3], s[28:29], 0, v[156:157]
	v_lshl_add_u64 v[8:9], s[26:27], 0, v[160:161]
	v_lshl_add_u64 v[10:11], s[26:27], 0, v[158:159]
	s_cselect_b64 s[14:15], -1, 0
	s_cmp_lg_u32 s11, 1
	s_cbranch_scc1 .LBB0_1209
	s_barrier

.Lxi_9:
	s_and_saveexec_b64 s[8:9], vcc
	s_cbranch_execz .LBB0_550
	s_bcnt1_i32_b64 s4, s[6:7]
	v_readlane_b32 s6, v254, 28
	v_mov_b32_e32 v0, s4
	v_readlane_b32 s7, v254, 29
	s_nop 4
	global_atomic_add v181, v0, s[6:7]
	s_branch .LBB0_550
